# v203 + P10 fused epilogue: the three later residual load groups issued together with the first (banked, copied at the old sites)
# baseline (speedup 1.0000x reference)
.LBB0_713:
	v_lshrrev_b32_e32 v130, 4, v1
	s_lshl_b32 s16, s28, 5
	s_lshl_b32 s0, s12, 8
	s_or_b32 s0, s0, s16
	v_lshlrev_b32_e32 v152, 2, v130
	s_lshl_b32 s18, s11, 8
	v_or_b32_e32 v130, s0, v152
	s_ashr_i32 s0, s11, 4
	s_add_i32 s2, s18, s42
	s_mul_hi_i32 s1, s0, 0x9000
	s_mul_i32 s0, s0, 0x9000
	s_add_u32 s0, s58, s0
	s_addc_u32 s1, s59, s1
	v_ashrrev_i32_e32 v131, 31, v130
	v_lshl_add_u64 v[132:133], v[130:131], 2, s[0:1]
	s_mov_b64 s[0:1], 0x108000
	v_lshl_add_u64 v[140:141], v[132:133], 0, s[0:1]
	s_mov_b32 s0, 0x108000
	v_add_co_u32_e32 v136, vcc, s0, v132
	v_bfe_u32 v142, v1, 4, 1
	s_nop 0
	v_addc_co_u32_e32 v137, vcc, 0, v133, vcc
	s_barrier
	global_load_dwordx4 v[132:135], v[140:141], off offset:64
	global_load_dwordx4 v[154:157], v[140:141], off offset:512
	s_nop 0
	global_load_dwordx4 v[136:139], v[136:137], off
	s_nop 0
	global_load_dwordx4 v[158:161], v[140:141], off offset:576
	v_lshlrev_b32_e32 v140, 2, v142
	v_or_b32_e32 v153, s2, v151
	v_sub_co_u32_e32 v140, vcc, v130, v140
	v_lshlrev_b32_e32 v178, 4, v142
	s_nop 0
	v_subbrev_co_u32_e32 v141, vcc, 0, v131, vcc
	v_or_b32_e32 v142, v153, v178
	v_ashrrev_i32_e32 v143, 31, v142
	v_lshl_add_u64 v[140:141], v[140:141], 1, s[58:59]
	s_mov_b64 s[0:1], 0xc400000
	v_lshl_add_u64 v[148:149], v[140:141], 0, s[0:1]
	v_lshlrev_b64 v[140:141], 11, v[142:143]
	v_lshl_add_u64 v[140:141], v[148:149], 0, v[140:141]
	global_load_dwordx4 v[162:165], v[140:141], off nt
	global_load_dwordx4 v[166:169], v[140:141], off offset:32 nt
	global_load_dwordx4 v[170:173], v[140:141], off offset:256 nt
	global_load_dwordx4 v[174:177], v[140:141], off offset:288 nt
	s_mov_b32 s99, 0
	s_mov_b32 s98, 0x10000
	v_lshl_add_u64 v[236:237], v[140:141], 0, s[98:99]
	s_mov_b32 s98, 0x40000
	v_lshl_add_u64 v[238:239], v[140:141], 0, s[98:99]
	s_mov_b32 s98, 0x50000
	v_lshl_add_u64 v[240:241], v[140:141], 0, s[98:99]
	global_load_dwordx4 v[188:191], v[236:237], off nt
	global_load_dwordx4 v[192:195], v[236:237], off offset:32 nt
	global_load_dwordx4 v[196:199], v[236:237], off offset:256 nt
	global_load_dwordx4 v[200:203], v[236:237], off offset:288 nt
	global_load_dwordx4 v[204:207], v[238:239], off nt
	global_load_dwordx4 v[208:211], v[238:239], off offset:32 nt
	global_load_dwordx4 v[212:215], v[238:239], off offset:256 nt
	global_load_dwordx4 v[216:219], v[238:239], off offset:288 nt
	global_load_dwordx4 v[220:223], v[240:241], off nt
	global_load_dwordx4 v[224:227], v[240:241], off offset:32 nt
	global_load_dwordx4 v[228:231], v[240:241], off offset:256 nt
	global_load_dwordx4 v[232:235], v[240:241], off offset:288 nt
	s_brev_b32 s0, 60
	v_and_or_b32 v179, v0, 16, 32
	s_waitcnt vmcnt(12)
	v_pk_mul_f32 v[142:143], v[132:133], s[0:1] op_sel_hi:[1,0]
	v_pk_mul_f32 v[140:141], v[134:135], s[0:1] op_sel_hi:[1,0]
	v_pk_mul_f32 v[146:147], v[136:137], s[0:1] op_sel_hi:[1,0]
	v_pk_mul_f32 v[132:133], v[158:159], s[0:1] op_sel_hi:[1,0]
	v_pk_mul_f32 v[144:145], v[138:139], s[0:1] op_sel_hi:[1,0]
	v_pk_mul_f32 v[138:139], v[154:155], s[0:1] op_sel_hi:[1,0]
	v_pk_mul_f32 v[134:135], v[160:161], s[0:1] op_sel_hi:[1,0]
	v_pk_mul_f32 v[136:137], v[156:157], s[0:1] op_sel_hi:[1,0]
	s_lshl_b32 s0, s28, 2
	s_add_i32 s2, s0, 0
	v_mov_b32_e32 v159, v164
	s_nop 1
	v_permlane16_swap_b32_e32 v162, v159
	v_lshlrev_b32_e32 v158, 16, v159
	v_and_b32_e32 v159, 0xffff0000, v159
	v_pk_fma_f32 v[118:119], v[118:119], v[146:147], v[158:159]
	v_mov_b32_e32 v158, v172
	v_lshlrev_b32_e32 v154, 16, v162
	v_and_b32_e32 v155, 0xffff0000, v162
	v_permlane16_swap_b32_e32 v170, v158
	v_mov_b32_e32 v161, v165
	v_pk_fma_f32 v[126:127], v[126:127], v[146:147], v[154:155]
	v_lshlrev_b32_e32 v154, 16, v170
	v_and_b32_e32 v155, 0xffff0000, v170
	v_permlane16_swap_b32_e32 v163, v161
	v_mov_b32_e32 v159, v173
	v_pk_fma_f32 v[110:111], v[110:111], v[138:139], v[154:155]
	v_lshlrev_b32_e32 v154, 16, v158
	v_and_b32_e32 v155, 0xffff0000, v158
	v_mov_b32_e32 v158, v176
	v_lshlrev_b32_e32 v156, 16, v163
	v_and_b32_e32 v157, 0xffff0000, v163
	v_permlane16_swap_b32_e32 v171, v159
	v_permlane16_swap_b32_e32 v174, v158
	v_pk_fma_f32 v[128:129], v[128:129], v[144:145], v[156:157]
	v_lshlrev_b32_e32 v156, 16, v171
	v_and_b32_e32 v157, 0xffff0000, v171
	v_pk_fma_f32 v[106:107], v[106:107], v[138:139], v[154:155]
	v_lshlrev_b32_e32 v154, 16, v174
	v_and_b32_e32 v155, 0xffff0000, v174
	v_pk_fma_f32 v[112:113], v[112:113], v[136:137], v[156:157]
	v_lshlrev_b32_e32 v156, 16, v159
	v_and_b32_e32 v157, 0xffff0000, v159
	v_mov_b32_e32 v159, v177
	v_pk_fma_f32 v[102:103], v[102:103], v[132:133], v[154:155]
	v_lshlrev_b32_e32 v154, 16, v158
	v_and_b32_e32 v155, 0xffff0000, v158
	v_permlane16_swap_b32_e32 v175, v159
	v_pk_fma_f32 v[98:99], v[98:99], v[132:133], v[154:155]
	v_or_b32_e32 v154, v153, v179
	v_permlane16_swap_b32_e32 v166, v168
	v_permlane16_swap_b32_e32 v167, v169
	v_pk_fma_f32 v[108:109], v[108:109], v[136:137], v[156:157]
	v_lshlrev_b32_e32 v156, 16, v175
	v_and_b32_e32 v157, 0xffff0000, v175
	v_ashrrev_i32_e32 v155, 31, v154
	v_lshlrev_b32_e32 v160, 16, v161
	v_and_b32_e32 v161, 0xffff0000, v161
	v_lshlrev_b32_e32 v162, 16, v166
	v_and_b32_e32 v163, 0xffff0000, v166
	v_lshlrev_b32_e32 v164, 16, v167
	v_and_b32_e32 v165, 0xffff0000, v167
	v_lshlrev_b32_e32 v166, 16, v168
	v_and_b32_e32 v167, 0xffff0000, v168
	v_lshlrev_b32_e32 v168, 16, v169
	v_and_b32_e32 v169, 0xffff0000, v169
	v_pk_fma_f32 v[104:105], v[104:105], v[134:135], v[156:157]
	v_lshlrev_b32_e32 v156, 16, v159
	v_and_b32_e32 v157, 0xffff0000, v159
	v_lshlrev_b64 v[154:155], 11, v[154:155]
	v_pk_fma_f32 v[120:121], v[120:121], v[144:145], v[160:161]
	v_pk_fma_f32 v[124:125], v[124:125], v[140:141], v[164:165]
	v_pk_fma_f32 v[122:123], v[122:123], v[142:143], v[162:163]
	v_pk_fma_f32 v[116:117], v[116:117], v[140:141], v[168:169]
	v_pk_fma_f32 v[114:115], v[114:115], v[142:143], v[166:167]
	v_pk_fma_f32 v[100:101], v[100:101], v[134:135], v[156:157]
	v_lshl_add_u64 v[166:167], v[148:149], 0, v[154:155]
	s_waitcnt vmcnt(8)
	v_mov_b32_e32 v154, v188
	v_mov_b32_e32 v155, v189
	v_mov_b32_e32 v156, v190
	v_mov_b32_e32 v157, v191
	v_mov_b32_e32 v158, v192
	v_mov_b32_e32 v159, v193
	v_mov_b32_e32 v160, v194
	v_mov_b32_e32 v161, v195
	v_mov_b32_e32 v162, v196
	v_mov_b32_e32 v163, v197
	v_mov_b32_e32 v164, v198
	v_mov_b32_e32 v165, v199
	v_mov_b32_e32 v166, v200
	v_mov_b32_e32 v167, v201
	v_mov_b32_e32 v168, v202
	v_mov_b32_e32 v169, v203
	s_nop 0
	v_add_u32_e32 v153, 0x80, v153
	s_nop 0
	v_mov_b32_e32 v170, v156
	s_nop 0
	v_mov_b32_e32 v175, v160
	v_mov_b32_e32 v177, v161
	s_nop 0
	v_permlane16_swap_b32_e32 v158, v175
	v_permlane16_swap_b32_e32 v159, v177
	v_mov_b32_e32 v171, v157
	v_lshlrev_b32_e32 v172, 16, v158
	v_and_b32_e32 v173, 0xffff0000, v158
	v_lshlrev_b32_e32 v158, 16, v159
	v_and_b32_e32 v159, 0xffff0000, v159
	v_permlane16_swap_b32_e32 v154, v170
	v_permlane16_swap_b32_e32 v155, v171
	v_pk_fma_f32 v[92:93], v[92:93], v[140:141], v[158:159]
	s_nop 0
	v_mov_b32_e32 v158, v164
	v_lshlrev_b32_e32 v156, 16, v154
	v_and_b32_e32 v157, 0xffff0000, v154
	v_lshlrev_b32_e32 v154, 16, v155
	v_and_b32_e32 v155, 0xffff0000, v155
	v_permlane16_swap_b32_e32 v162, v158
	v_pk_fma_f32 v[96:97], v[96:97], v[144:145], v[154:155]
	v_lshlrev_b32_e32 v154, 16, v162
	v_and_b32_e32 v155, 0xffff0000, v162
	v_mov_b32_e32 v159, v165
	v_pk_fma_f32 v[78:79], v[78:79], v[138:139], v[154:155]
	v_lshlrev_b32_e32 v154, 16, v158
	v_and_b32_e32 v155, 0xffff0000, v158
	s_nop 0
	v_mov_b32_e32 v158, v168
	v_permlane16_swap_b32_e32 v163, v159
	s_nop 0
	v_permlane16_swap_b32_e32 v166, v158
	v_pk_fma_f32 v[94:95], v[94:95], v[146:147], v[156:157]
	v_lshlrev_b32_e32 v156, 16, v163
	v_and_b32_e32 v157, 0xffff0000, v163
	v_pk_fma_f32 v[74:75], v[74:75], v[138:139], v[154:155]
	v_lshlrev_b32_e32 v154, 16, v166
	v_and_b32_e32 v155, 0xffff0000, v166
	v_pk_fma_f32 v[80:81], v[80:81], v[136:137], v[156:157]
	v_lshlrev_b32_e32 v156, 16, v159
	v_and_b32_e32 v157, 0xffff0000, v159
	v_mov_b32_e32 v159, v169
	v_pk_fma_f32 v[70:71], v[70:71], v[132:133], v[154:155]
	v_lshlrev_b32_e32 v154, 16, v158
	v_and_b32_e32 v155, 0xffff0000, v158
	v_permlane16_swap_b32_e32 v167, v159
	v_pk_fma_f32 v[66:67], v[66:67], v[132:133], v[154:155]
	v_or_b32_e32 v154, v153, v178
	v_pk_fma_f32 v[76:77], v[76:77], v[136:137], v[156:157]
	v_lshlrev_b32_e32 v156, 16, v167
	v_and_b32_e32 v157, 0xffff0000, v167
	v_ashrrev_i32_e32 v155, 31, v154
	v_lshlrev_b32_e32 v160, 16, v170
	v_and_b32_e32 v161, 0xffff0000, v170
	v_lshlrev_b32_e32 v170, 16, v171
	v_and_b32_e32 v171, 0xffff0000, v171
	v_lshlrev_b32_e32 v174, 16, v175
	v_and_b32_e32 v175, 0xffff0000, v175
	v_lshlrev_b32_e32 v176, 16, v177
	v_and_b32_e32 v177, 0xffff0000, v177
	v_pk_fma_f32 v[72:73], v[72:73], v[134:135], v[156:157]
	v_lshlrev_b32_e32 v156, 16, v159
	v_and_b32_e32 v157, 0xffff0000, v159
	v_lshlrev_b64 v[154:155], 11, v[154:155]
	v_pk_fma_f32 v[88:89], v[88:89], v[144:145], v[170:171]
	v_pk_fma_f32 v[86:87], v[86:87], v[146:147], v[160:161]
	v_pk_fma_f32 v[90:91], v[90:91], v[142:143], v[172:173]
	v_pk_fma_f32 v[84:85], v[84:85], v[140:141], v[176:177]
	v_pk_fma_f32 v[82:83], v[82:83], v[142:143], v[174:175]
	v_pk_fma_f32 v[68:69], v[68:69], v[134:135], v[156:157]
	v_lshl_add_u64 v[166:167], v[148:149], 0, v[154:155]
	s_waitcnt vmcnt(4)
	v_mov_b32_e32 v154, v204
	v_mov_b32_e32 v155, v205
	v_mov_b32_e32 v156, v206
	v_mov_b32_e32 v157, v207
	v_mov_b32_e32 v158, v208
	v_mov_b32_e32 v159, v209
	v_mov_b32_e32 v160, v210
	v_mov_b32_e32 v161, v211
	v_mov_b32_e32 v162, v212
	v_mov_b32_e32 v163, v213
	v_mov_b32_e32 v164, v214
	v_mov_b32_e32 v165, v215
	v_mov_b32_e32 v166, v216
	v_mov_b32_e32 v167, v217
	v_mov_b32_e32 v168, v218
	v_mov_b32_e32 v169, v219
	s_nop 0
	s_nop 0
	v_mov_b32_e32 v170, v156
	s_nop 0
	v_mov_b32_e32 v175, v160
	v_mov_b32_e32 v177, v161
	s_nop 0
	v_permlane16_swap_b32_e32 v158, v175
	v_permlane16_swap_b32_e32 v159, v177
	v_lshlrev_b32_e32 v172, 16, v158
	v_and_b32_e32 v173, 0xffff0000, v158
	v_lshlrev_b32_e32 v158, 16, v159
	v_and_b32_e32 v159, 0xffff0000, v159
	v_mov_b32_e32 v171, v157
	v_permlane16_swap_b32_e32 v154, v170
	v_pk_fma_f32 v[60:61], v[60:61], v[140:141], v[158:159]
	s_nop 0
	v_mov_b32_e32 v158, v165
	v_permlane16_swap_b32_e32 v155, v171
	v_lshlrev_b32_e32 v156, 16, v154
	v_and_b32_e32 v157, 0xffff0000, v154
	v_permlane16_swap_b32_e32 v163, v158
	v_lshlrev_b32_e32 v154, 16, v155
	v_and_b32_e32 v155, 0xffff0000, v155
	v_pk_fma_f32 v[62:63], v[62:63], v[146:147], v[156:157]
	v_permlane16_swap_b32_e32 v162, v164
	v_lshlrev_b32_e32 v156, 16, v163
	v_and_b32_e32 v157, 0xffff0000, v163
	v_pk_fma_f32 v[64:65], v[64:65], v[144:145], v[154:155]
	v_lshlrev_b32_e32 v154, 16, v162
	v_and_b32_e32 v155, 0xffff0000, v162
	v_pk_fma_f32 v[48:49], v[48:49], v[136:137], v[156:157]
	v_lshlrev_b32_e32 v156, 16, v158
	v_and_b32_e32 v157, 0xffff0000, v158
	s_nop 0
	v_mov_b32_e32 v158, v168
	v_pk_fma_f32 v[46:47], v[46:47], v[138:139], v[154:155]
	v_lshlrev_b32_e32 v154, 16, v164
	v_and_b32_e32 v155, 0xffff0000, v164
	v_permlane16_swap_b32_e32 v166, v158
	v_pk_fma_f32 v[42:43], v[42:43], v[138:139], v[154:155]
	v_lshlrev_b32_e32 v154, 16, v166
	v_and_b32_e32 v155, 0xffff0000, v166
	v_mov_b32_e32 v159, v169
	v_pk_fma_f32 v[38:39], v[38:39], v[132:133], v[154:155]
	v_lshlrev_b32_e32 v154, 16, v158
	v_and_b32_e32 v155, 0xffff0000, v158
	v_permlane16_swap_b32_e32 v167, v159
	v_pk_fma_f32 v[34:35], v[34:35], v[132:133], v[154:155]
	v_or_b32_e32 v154, v153, v179
	v_pk_fma_f32 v[44:45], v[44:45], v[136:137], v[156:157]
	v_lshlrev_b32_e32 v156, 16, v167
	v_and_b32_e32 v157, 0xffff0000, v167
	v_ashrrev_i32_e32 v155, 31, v154
	v_lshlrev_b32_e32 v160, 16, v170
	v_and_b32_e32 v161, 0xffff0000, v170
	v_lshlrev_b32_e32 v170, 16, v171
	v_and_b32_e32 v171, 0xffff0000, v171
	v_lshlrev_b32_e32 v174, 16, v175
	v_and_b32_e32 v175, 0xffff0000, v175
	v_lshlrev_b32_e32 v176, 16, v177
	v_and_b32_e32 v177, 0xffff0000, v177
	v_pk_fma_f32 v[40:41], v[40:41], v[134:135], v[156:157]
	v_lshlrev_b32_e32 v156, 16, v159
	v_and_b32_e32 v157, 0xffff0000, v159
	v_lshlrev_b64 v[154:155], 11, v[154:155]
	v_pk_fma_f32 v[56:57], v[56:57], v[144:145], v[170:171]
	v_pk_fma_f32 v[54:55], v[54:55], v[146:147], v[160:161]
	v_pk_fma_f32 v[58:59], v[58:59], v[142:143], v[172:173]
	v_pk_fma_f32 v[52:53], v[52:53], v[140:141], v[176:177]
	v_pk_fma_f32 v[50:51], v[50:51], v[142:143], v[174:175]
	v_pk_fma_f32 v[36:37], v[36:37], v[134:135], v[156:157]
	v_lshl_add_u64 v[148:149], v[148:149], 0, v[154:155]
	s_waitcnt vmcnt(0)
	v_mov_b32_e32 v154, v220
	v_mov_b32_e32 v155, v221
	v_mov_b32_e32 v156, v222
	v_mov_b32_e32 v157, v223
	v_mov_b32_e32 v158, v224
	v_mov_b32_e32 v159, v225
	v_mov_b32_e32 v160, v226
	v_mov_b32_e32 v161, v227
	v_mov_b32_e32 v162, v228
	v_mov_b32_e32 v163, v229
	v_mov_b32_e32 v164, v230
	v_mov_b32_e32 v165, v231
	v_mov_b32_e32 v166, v232
	v_mov_b32_e32 v167, v233
	v_mov_b32_e32 v168, v234
	v_mov_b32_e32 v169, v235
	s_nop 0
	v_mov_b32_e32 v153, v156
	v_mov_b32_e32 v170, v157
	s_nop 0
	v_mov_b32_e32 v173, v160
	v_mov_b32_e32 v175, v161
	v_permlane16_swap_b32_e32 v154, v153
	v_permlane16_swap_b32_e32 v155, v170
	v_permlane16_swap_b32_e32 v158, v173
	v_permlane16_swap_b32_e32 v159, v175
	s_nop 0
	v_permlane16_swap_b32_e32 v162, v164
	v_lshlrev_b32_e32 v148, 16, v154
	v_and_b32_e32 v149, 0xffff0000, v154
	v_lshlrev_b32_e32 v154, 16, v155
	v_and_b32_e32 v155, 0xffff0000, v155
	v_lshlrev_b32_e32 v160, 16, v170
	v_and_b32_e32 v161, 0xffff0000, v170
	v_lshlrev_b32_e32 v170, 16, v158
	v_and_b32_e32 v171, 0xffff0000, v158
	v_lshlrev_b32_e32 v158, 16, v159
	v_and_b32_e32 v159, 0xffff0000, v159
	v_lshlrev_b32_e32 v174, 16, v175
	v_and_b32_e32 v175, 0xffff0000, v175
	v_pk_fma_f32 v[32:33], v[32:33], v[144:145], v[154:155]
	v_pk_fma_f32 v[24:25], v[24:25], v[144:145], v[160:161]
	v_pk_fma_f32 v[28:29], v[28:29], v[140:141], v[158:159]
	v_pk_fma_f32 v[20:21], v[20:21], v[140:141], v[174:175]
	v_mov_b32_e32 v144, v165
	v_lshlrev_b32_e32 v140, 16, v162
	v_and_b32_e32 v141, 0xffff0000, v162
	v_lshlrev_b32_e32 v172, 16, v173
	v_and_b32_e32 v173, 0xffff0000, v173
	v_permlane16_swap_b32_e32 v163, v144
	v_pk_fma_f32 v[14:15], v[14:15], v[138:139], v[140:141]
	v_lshlrev_b32_e32 v140, 16, v164
	v_and_b32_e32 v141, 0xffff0000, v164
	v_pk_fma_f32 v[26:27], v[26:27], v[142:143], v[170:171]
	v_pk_fma_f32 v[18:19], v[18:19], v[142:143], v[172:173]
	v_lshlrev_b32_e32 v142, 16, v163
	v_and_b32_e32 v143, 0xffff0000, v163
	v_pk_fma_f32 v[10:11], v[10:11], v[138:139], v[140:141]
	s_nop 0
	v_mov_b32_e32 v140, v168
	v_mov_b32_e32 v141, v169
	v_pk_fma_f32 v[16:17], v[16:17], v[136:137], v[142:143]
	v_lshlrev_b32_e32 v142, 16, v144
	v_and_b32_e32 v143, 0xffff0000, v144
	v_permlane16_swap_b32_e32 v166, v140
	v_permlane16_swap_b32_e32 v167, v141
	v_pk_fma_f32 v[12:13], v[12:13], v[136:137], v[142:143]
	v_lshlrev_b32_e32 v136, 16, v166
	v_and_b32_e32 v137, 0xffff0000, v166
	v_lshlrev_b32_e32 v138, 16, v167
	v_and_b32_e32 v139, 0xffff0000, v167
	v_pk_fma_f32 v[8:9], v[8:9], v[134:135], v[138:139]
	v_pk_fma_f32 v[6:7], v[6:7], v[132:133], v[136:137]
	v_lshlrev_b32_e32 v136, 16, v140
	v_and_b32_e32 v137, 0xffff0000, v140
	v_lshlrev_b32_e32 v138, 16, v141
	v_and_b32_e32 v139, 0xffff0000, v141
	v_pk_fma_f32 v[4:5], v[4:5], v[134:135], v[138:139]
	v_pk_fma_f32 v[2:3], v[2:3], v[132:133], v[136:137]
	v_mul_f32_e32 v135, v127, v127
	v_mul_f32_e32 v136, v129, v129
	v_fmac_f32_e32 v135, v126, v126
	v_fmac_f32_e32 v136, v128, v128
	v_add_f32_e32 v135, v135, v136
	v_mul_f32_e32 v136, v123, v123
	v_mul_f32_e32 v137, v125, v125
	v_fmac_f32_e32 v136, v122, v122
	v_fmac_f32_e32 v137, v124, v124
	v_add_f32_e32 v136, v136, v137
	v_mbcnt_lo_u32_b32 v132, -1, 0
	v_add_f32_e32 v135, v135, v136
	v_mul_f32_e32 v136, v111, v111
	v_mul_f32_e32 v137, v113, v113
	v_mbcnt_hi_u32_b32 v133, -1, v132
	v_fmac_f32_e32 v136, v110, v110
	v_fmac_f32_e32 v137, v112, v112
	v_and_b32_e32 v134, 64, v133
	v_add_f32_e32 v136, v136, v137
	v_xor_b32_e32 v132, 16, v133
	v_add_u32_e32 v134, 64, v134
	v_add_f32_e32 v135, v136, v135
	v_mul_f32_e32 v136, v103, v103
	v_mul_f32_e32 v137, v105, v105
	v_cmp_lt_i32_e32 vcc, v132, v134
	v_fmac_f32_e32 v136, v102, v102
	v_fmac_f32_e32 v137, v104, v104
	v_cndmask_b32_e32 v132, v133, v132, vcc
	v_add_f32_e32 v136, v136, v137
	v_lshlrev_b32_e32 v132, 2, v132
	v_add_f32_e32 v135, v136, v135
	ds_bpermute_b32 v136, v132, v135
	v_xor_b32_e32 v137, 32, v133
	v_cmp_lt_i32_e32 vcc, v137, v134
	v_lshlrev_b32_e32 v156, 16, v153
	v_and_b32_e32 v157, 0xffff0000, v153
	v_cndmask_b32_e32 v133, v133, v137, vcc
	v_lshlrev_b32_e32 v133, 2, v133
	s_waitcnt lgkmcnt(0)
	v_add_f32_e32 v134, v135, v136
	ds_bpermute_b32 v135, v133, v134
	v_pk_fma_f32 v[30:31], v[30:31], v[146:147], v[148:149]
	v_pk_fma_f32 v[22:23], v[22:23], v[146:147], v[156:157]
	v_cmp_gt_u32_e32 vcc, 16, v1
	s_and_saveexec_b64 s[0:1], vcc
	s_cbranch_execz .LBB0_715
	s_lshl_b32 s3, s13, 10
	s_add_i32 s3, s2, s3
	v_lshl_add_u32 v136, v151, 4, s3
	s_waitcnt lgkmcnt(0)
	v_add_f32_e32 v134, v134, v135
	ds_write_b32 v136, v134
